# NA loop: persistent seed tuple, shared bias table base for both score blocks, unused per-element address math removed
# baseline (speedup 1.0000x reference)
; DI f32x16 mfma32(bf16x8 a, bf16x8 b, f32x16 c) { return __builtin_amdgcn_mfma_f32_32x32x16_bf16(a, b, c, 0, 0, 0); }
; DI void attn_na_unit(const Params& p, int li, int b, int r, int hp, char* smem) {
;     ...
;     f32x16 s0, s1;
; #pragma unroll
;     for (int i = 0; i < 16; ++i) { s0[i] = -m; s1[i] = -m; }
;     {
;       bf16x8 kf[8];
; #pragma unroll
;       for (int s = 0; s < 4; ++s) {
;         kf[2 * s] = *(const bf16x8*)(ks + r32 * KR + (hs * 64 + s * 16 + hh * 8) * 2);
;         kf[2 * s + 1] = *(const bf16x8*)(ks + (32 + r32) * KR + (hs * 64 + s * 16 + hh * 8) * 2);
;       }
;       __builtin_amdgcn_sched_barrier(0); __builtin_amdgcn_s_setprio(1);
; #pragma unroll
;       for (int s = 0; s < 4; ++s) { s0 = mfma32(kf[2 * s], qf[s], s0); s1 = mfma32(kf[2 * s + 1], qf[s], s1); }
;     __builtin_amdgcn_s_setprio(0);
; }
;     const int drow = rs + kt - r + 7;
;     const float* trow = tab + hs * 465 + drow * 31;
; #pragma unroll
;     for (int i = 0; i < 16; ++i) {
;       const int kc0 = (i & 3) + 8 * (i >> 2) + 4 * hh;
;       const int kc1 = kc0 + 32;
;       const bool v0 = (unsigned)(kc0 - cs) < 16u;
;       const bool v1 = (unsigned)(kc1 - cs) < 16u;
;       const int d0 = v0 ? (kc0 - wq + 15) : 0;
;       const int d1 = v1 ? (kc1 - wq + 15) : 0;
;       const float b0 = trow[d0], b1 = trow[d1];
.LBB0_1537:
	v_lshlrev_b32_e32 v126, 6, v39
	v_mul_u32_u24_e32 v39, 0x110, v33
	v_mul_u32_u24_e32 v42, 0x140, v33
	v_add_f32_e32 v33, 0, v50
	v_add_f32_e32 v50, 0, v60
	v_mul_f32_e32 v34, v50, v34
	v_add_f32_e32 v60, v33, v61
	v_cndmask_b32_e64 v128, v60, v33, s[6:7]
	v_xor_b32_e32 v220, 0x80000000, v128
	v_mov_b32_e32 v221, v220
	v_mov_b64_e32 v[222:223], v[220:221]
	v_mov_b64_e32 v[224:225], v[220:221]
	v_mov_b64_e32 v[226:227], v[220:221]
	v_mov_b64_e32 v[228:229], v[220:221]
	v_mov_b64_e32 v[230:231], v[220:221]
	v_mov_b64_e32 v[232:233], v[220:221]
	v_mov_b64_e32 v[234:235], v[220:221]
	v_cndmask_b32_e64 v127, v34, v50, s[6:7]
	s_movk_i32 s6, 0x7c
	v_mad_u32_u24 v34, v38, s6, v41
	v_add_u32_e32 v32, v34, v32
	v_lshlrev_b32_e32 v37, 2, v37
	v_mul_lo_u32 v36, v36, s6
	v_sub_u32_e32 v32, v32, v37
	v_lshlrev_b32_e32 v37, 1, v35
	v_sub_u32_e32 v32, v32, v36
	v_and_b32_e32 v37, 0x80, v37
	v_sub_u32_e32 v32, v32, v37
	v_add_u32_e32 v130, v120, v32
	v_and_b32_e32 v32, 15, v35
	v_and_b32_e32 v33, 3, v121
	v_lshlrev_b32_e32 v32, 4, v32
	v_lshlrev_b64 v[62:63], 9, v[144:145]
	v_lshl_add_u32 v38, v43, 2, v34
	v_lshl_or_b32 v144, v33, 8, v32
	v_sub_u32_e32 v38, v38, v36
	v_lshl_add_u64 v[32:33], v[62:63], 1, v[144:145]
	v_add_u32_e32 v129, v119, v38
	v_lshl_add_u64 v[114:115], s[34:35], 0, v[32:33]
	s_movk_i32 s9, 0xfc9c
	v_add_u32_e32 v144, v40, v39
	v_add_u32_e32 v148, v40, v42
	v_readfirstlane_b32 s100, v182
	s_branch .LBB0_1539
.LBB0_1538:
	v_add_f32_e32 v33, v127, v33
	v_mul_f32_e32 v32, v33, v32
	v_add_f32_e32 v34, v128, v34
	v_cndmask_b32_e64 v128, v34, v128, s[6:7]
	v_cndmask_b32_e64 v127, v32, v33, s[6:7]
	s_cmp_lg_u64 s[6:7], 0
	s_cbranch_scc1 .Lna_seed_ok
	v_xor_b32_e32 v220, 0x80000000, v128
	v_mov_b32_e32 v221, v220
	v_mov_b64_e32 v[222:223], v[220:221]
	v_mov_b64_e32 v[224:225], v[220:221]
	v_mov_b64_e32 v[226:227], v[220:221]
	v_mov_b64_e32 v[228:229], v[220:221]
	v_mov_b64_e32 v[230:231], v[220:221]
	v_mov_b64_e32 v[232:233], v[220:221]
	v_mov_b64_e32 v[234:235], v[220:221]
.Lna_seed_ok:
	s_addk_i32 s9, 0x7c
	s_mov_b64 s[6:7], 0x10000
	s_cmp_lg_u32 s9, 0
	v_lshl_add_u64 v[114:115], v[114:115], 0, s[6:7]
	s_cbranch_scc0 .LBB0_1500

; DI f32x16 mfma32(bf16x8 a, bf16x8 b, f32x16 c) { return __builtin_amdgcn_mfma_f32_32x32x16_bf16(a, b, c, 0, 0, 0); }
; DI void attn_na_unit(const Params& p, int li, int b, int r, int hp, char* smem) {
;     ...
;     f32x16 s0, s1;
; #pragma unroll
;     for (int i = 0; i < 16; ++i) { s0[i] = -m; s1[i] = -m; }
;     {
;       bf16x8 kf[8];
; #pragma unroll
;       for (int s = 0; s < 4; ++s) {
;         kf[2 * s] = *(const bf16x8*)(ks + r32 * KR + (hs * 64 + s * 16 + hh * 8) * 2);
;         kf[2 * s + 1] = *(const bf16x8*)(ks + (32 + r32) * KR + (hs * 64 + s * 16 + hh * 8) * 2);
;       }
;       __builtin_amdgcn_sched_barrier(0); __builtin_amdgcn_s_setprio(1);
; #pragma unroll
;       for (int s = 0; s < 4; ++s) { s0 = mfma32(kf[2 * s], qf[s], s0); s1 = mfma32(kf[2 * s + 1], qf[s], s1); }
;     __builtin_amdgcn_s_setprio(0);
; }
;     const int drow = rs + kt - r + 7;
;     const float* trow = tab + hs * 465 + drow * 31;
; #pragma unroll
;     for (int i = 0; i < 16; ++i) {
;       const int kc0 = (i & 3) + 8 * (i >> 2) + 4 * hh;
;       const int kc1 = kc0 + 32;
;       const bool v0 = (unsigned)(kc0 - cs) < 16u;
;       const bool v1 = (unsigned)(kc1 - cs) < 16u;
;       const int d0 = v0 ? (kc0 - wq + 15) : 0;
;       const int d1 = v1 ? (kc1 - wq + 15) : 0;
;       const float b0 = trow[d0], b1 = trow[d1];
;       s0[i] = v0 ? s0[i] + b0 : -1e30f;
;       s1[i] = v1 ? s1[i] + b1 : -1e30f;
;     }
.LBB0_1541:
	ds_read_b128 v[150:153], v123
	ds_read_b128 v[154:157], v123 offset:32
	ds_read_b128 v[158:161], v123 offset:8704
	ds_read_b128 v[162:165], v123 offset:8736
	ds_read_b128 v[166:169], v123 offset:64
	ds_read_b128 v[170:173], v123 offset:96
	ds_read_b128 v[174:177], v123 offset:8768
	ds_read_b128 v[178:181], v123 offset:8800
	s_setprio 1
	s_waitcnt lgkmcnt(7)
	v_mfma_f32_32x32x16_bf16 v[48:63], v[150:153], v[64:67], v[220:235]
	s_waitcnt lgkmcnt(5)
	v_mfma_f32_32x32x16_bf16 v[32:47], v[158:161], v[64:67], v[220:235]
	v_mfma_f32_32x32x16_bf16 v[48:63], v[154:157], v[68:71], v[48:63]
	s_waitcnt lgkmcnt(4)
	v_mfma_f32_32x32x16_bf16 v[32:47], v[162:165], v[68:71], v[32:47]
	s_waitcnt lgkmcnt(3)
	v_mfma_f32_32x32x16_bf16 v[48:63], v[166:169], v[72:75], v[48:63]
	s_waitcnt lgkmcnt(1)
	v_mfma_f32_32x32x16_bf16 v[32:47], v[174:177], v[72:75], v[32:47]
	v_mfma_f32_32x32x16_bf16 v[48:63], v[170:173], v[76:79], v[48:63]
	s_waitcnt lgkmcnt(0)
	v_mfma_f32_32x32x16_bf16 v[32:47], v[178:181], v[76:79], v[32:47]
	s_setprio 0
	s_bitcmp1_b32 s100, 6
	s_cbranch_scc1 .Lna_el_q1
	v_add_u32_e32 v149, s9, v130
	ds_read_b32 v150, v149 offset:868
	ds_read_b32 v151, v149 offset:872
	ds_read_b32 v152, v149 offset:876
	ds_read_b32 v153, v149 offset:880
	ds_read_b32 v154, v149 offset:900
	ds_read_b32 v155, v149 offset:904
	ds_read_b32 v156, v149 offset:908
	ds_read_b32 v157, v149 offset:912
	ds_read_b32 v158, v149 offset:932
	ds_read_b32 v159, v149 offset:936
	ds_read_b32 v160, v149 offset:940
	ds_read_b32 v161, v149 offset:944
	ds_read_b32 v162, v149 offset:964
	ds_read_b32 v163, v149 offset:968
	ds_read_b32 v164, v149 offset:972
	ds_read_b32 v165, v149 offset:976
	ds_read_b32 v166, v149 offset:996
	ds_read_b32 v167, v149 offset:1000
	ds_read_b32 v168, v149 offset:1004
	ds_read_b32 v169, v149 offset:1008
	s_waitcnt lgkmcnt(0)
	s_nop 7
	v_add_f32_e32 v48, v48, v150
	v_cndmask_b32_e64 v48, v195, v48, s[76:77]
	v_exp_f32_e32 v48, v48
	v_add_f32_e32 v49, v49, v151
	v_cndmask_b32_e64 v49, v195, v49, s[90:91]
	v_exp_f32_e32 v49, v49
	v_add_f32_e32 v50, v50, v152
	v_cndmask_b32_e64 v50, v195, v50, s[96:97]
	v_exp_f32_e32 v50, v50
	v_add_f32_e32 v51, v51, v153
	v_cndmask_b32_e64 v51, v195, v51, s[70:71]
	v_exp_f32_e32 v51, v51
	v_add_f32_e32 v52, v52, v154
	v_cndmask_b32_e64 v52, v195, v52, s[64:65]
	v_exp_f32_e32 v52, v52
	v_add_f32_e32 v53, v53, v155
	v_cndmask_b32_e64 v53, v195, v53, s[66:67]
	v_exp_f32_e32 v53, v53
	v_add_f32_e32 v54, v54, v156
	v_cndmask_b32_e64 v54, v195, v54, s[60:61]
	v_exp_f32_e32 v54, v54
	v_add_f32_e32 v55, v55, v157
	v_cndmask_b32_e64 v55, v195, v55, s[68:69]
	v_exp_f32_e32 v55, v55
	v_add_f32_e32 v56, v56, v158
	v_cndmask_b32_e64 v56, v195, v56, s[52:53]
	v_exp_f32_e32 v56, v56
	v_add_f32_e32 v57, v57, v159
	v_cndmask_b32_e64 v57, v195, v57, s[54:55]
	v_exp_f32_e32 v57, v57
	v_add_f32_e32 v58, v58, v160
	v_cndmask_b32_e64 v58, v195, v58, s[40:41]
	v_exp_f32_e32 v58, v58
	v_add_f32_e32 v59, v59, v161
	v_cndmask_b32_e64 v59, v195, v59, s[42:43]
	v_exp_f32_e32 v59, v59
	v_add_f32_e32 v60, v60, v162
	v_cndmask_b32_e64 v60, v195, v60, s[36:37]
	v_exp_f32_e32 v60, v60
	v_add_f32_e32 v61, v61, v163
	v_cndmask_b32_e64 v61, v195, v61, s[46:47]
	v_exp_f32_e32 v61, v61
	v_add_f32_e32 v62, v62, v164
	v_cndmask_b32_e64 v62, v195, v62, s[86:87]
	v_exp_f32_e32 v62, v62
	v_add_f32_e32 v63, v63, v165
	v_cndmask_b32_e64 v63, v195, v63, s[4:5]
	v_exp_f32_e32 v63, v63
	v_add_f32_e32 v32, v32, v166
	v_cndmask_b32_e64 v32, v195, v32, s[78:79]
	v_exp_f32_e32 v32, v32
	v_add_f32_e32 v33, v33, v167
	v_cndmask_b32_e64 v33, v195, v33, s[92:93]
	v_exp_f32_e32 v33, v33
	v_add_f32_e32 v34, v34, v168
	v_cndmask_b32_e64 v34, v195, v34, s[94:95]
	v_exp_f32_e32 v34, v34
	v_add_f32_e32 v35, v35, v169
	v_cndmask_b32_e64 v35, v195, v35, s[72:73]
	v_exp_f32_e32 v35, v35
	v_add_f32_e32 v149, 0, v48
	v_add_f32_e32 v149, v149, v49
	v_add_f32_e32 v149, v149, v50
	v_add_f32_e32 v149, v149, v51
	v_add_f32_e32 v149, v149, v52
	v_add_f32_e32 v149, v149, v53
	v_add_f32_e32 v149, v149, v54
	v_add_f32_e32 v149, v149, v55
	v_add_f32_e32 v149, v149, v56
	v_add_f32_e32 v149, v149, v57
	v_add_f32_e32 v149, v149, v58
	v_add_f32_e32 v149, v149, v59
	v_add_f32_e32 v149, v149, v60
	v_add_f32_e32 v149, v149, v61
	v_add_f32_e32 v149, v149, v62
	v_add_f32_e32 v149, v149, v63
	v_add_f32_e32 v149, v149, v32
	v_add_f32_e32 v149, v149, v33
	v_add_f32_e32 v149, v149, v34
	v_add_f32_e32 v149, v149, v35
	v_cvt_pk_bf16_f32 v36, v48, v49
	v_cvt_pk_bf16_f32 v37, v50, v51
	v_cvt_pk_bf16_f32 v38, v52, v53
	v_cvt_pk_bf16_f32 v39, v54, v55
	v_cvt_pk_bf16_f32 v40, v56, v57
	v_cvt_pk_bf16_f32 v41, v58, v59
	v_cvt_pk_bf16_f32 v42, v60, v61
	v_cvt_pk_bf16_f32 v43, v62, v63
	v_cvt_pk_bf16_f32 v44, v32, v33
	v_cvt_pk_bf16_f32 v45, v34, v35
	v_mov_b32_e32 v46, 0
	v_mov_b32_e32 v47, 0
	v_mov_b32_e32 v33, v149
	s_branch .Lna_el_done
; DI bool softmax_tile(f32x16& s0, f32x16& s1, float& m, float& l, float& alpha, bf16x8* pf, int lane, bool first, bool check) {
;     ...
;   float sum = 0.f;
; #pragma unroll
;   for (int i = 0; i < 16; ++i) { s0[i] = __builtin_amdgcn_exp2f(s0[i]); sum += s0[i]; }
; #pragma unroll
;   for (int i = 0; i < 16; ++i) { s1[i] = __builtin_amdgcn_exp2f(s1[i]); sum += s1[i]; }
;   l += sum;
;   pf[0] = pack8(s0, 0); pf[1] = pack8(s0, 8); pf[2] = pack8(s1, 0); pf[3] = pack8(s1, 8);
; DI void attn_na_unit(const Params& p, int li, int b, int r, int hp, char* smem) {
;     ...
;     const int drow = rs + kt - r + 7;
;     const float* trow = tab + hs * 465 + drow * 31;
; #pragma unroll
;     for (int i = 0; i < 16; ++i) {
;       const int kc0 = (i & 3) + 8 * (i >> 2) + 4 * hh;
;       const int kc1 = kc0 + 32;
;       const bool v0 = (unsigned)(kc0 - cs) < 16u;
;       const bool v1 = (unsigned)(kc1 - cs) < 16u;
;       const int d0 = v0 ? (kc0 - wq + 15) : 0;
;       const int d1 = v1 ? (kc1 - wq + 15) : 0;
;       const float b0 = trow[d0], b1 = trow[d1];
;       s0[i] = v0 ? s0[i] + b0 : -1e30f;
;       s1[i] = v1 ? s1[i] + b1 : -1e30f;
;     }
.Lna_el_q1:
	v_add_u32_e32 v149, s9, v130
	ds_read_b32 v150, v149 offset:964
	ds_read_b32 v151, v149 offset:968
	ds_read_b32 v152, v149 offset:972
	ds_read_b32 v153, v149 offset:976
	ds_read_b32 v154, v149 offset:996
	ds_read_b32 v155, v149 offset:1000
	ds_read_b32 v156, v149 offset:1004
	ds_read_b32 v157, v149 offset:1008
	ds_read_b32 v158, v149 offset:1028
	ds_read_b32 v159, v149 offset:1032
	ds_read_b32 v160, v149 offset:1036
	ds_read_b32 v161, v149 offset:1040
	ds_read_b32 v162, v149 offset:1060
	ds_read_b32 v163, v149 offset:1064
	ds_read_b32 v164, v149 offset:1068
	ds_read_b32 v165, v149 offset:1072
	ds_read_b32 v166, v149 offset:1092
	ds_read_b32 v167, v149 offset:1096
	ds_read_b32 v168, v149 offset:1100
	ds_read_b32 v169, v149 offset:1104
	s_waitcnt lgkmcnt(0)
	s_nop 7
	v_add_f32_e32 v60, v60, v150
	v_cndmask_b32_e64 v60, v195, v60, s[36:37]
	v_exp_f32_e32 v60, v60
	v_add_f32_e32 v61, v61, v151
	v_cndmask_b32_e64 v61, v195, v61, s[46:47]
	v_exp_f32_e32 v61, v61
	v_add_f32_e32 v62, v62, v152
	v_cndmask_b32_e64 v62, v195, v62, s[86:87]
	v_exp_f32_e32 v62, v62
	v_add_f32_e32 v63, v63, v153
	v_cndmask_b32_e64 v63, v195, v63, s[4:5]
	v_exp_f32_e32 v63, v63
	v_add_f32_e32 v32, v32, v154
	v_cndmask_b32_e64 v32, v195, v32, s[78:79]
	v_exp_f32_e32 v32, v32
	v_add_f32_e32 v33, v33, v155
	v_cndmask_b32_e64 v33, v195, v33, s[92:93]
	v_exp_f32_e32 v33, v33
	v_add_f32_e32 v34, v34, v156
	v_cndmask_b32_e64 v34, v195, v34, s[94:95]
	v_exp_f32_e32 v34, v34
	v_add_f32_e32 v35, v35, v157
	v_cndmask_b32_e64 v35, v195, v35, s[72:73]
	v_exp_f32_e32 v35, v35
	v_add_f32_e32 v36, v36, v158
	v_cndmask_b32_e64 v36, v195, v36, s[80:81]
	v_exp_f32_e32 v36, v36
	v_add_f32_e32 v37, v37, v159
	v_cndmask_b32_e64 v37, v195, v37, s[74:75]
	v_exp_f32_e32 v37, v37
	v_add_f32_e32 v38, v38, v160
	v_cndmask_b32_e64 v38, v195, v38, s[58:59]
	v_exp_f32_e32 v38, v38
	v_add_f32_e32 v39, v39, v161
	v_cndmask_b32_e64 v39, v195, v39, s[48:49]
	v_exp_f32_e32 v39, v39
	v_add_f32_e32 v40, v40, v162
	v_cndmask_b32_e64 v40, v195, v40, s[50:51]
	v_exp_f32_e32 v40, v40
	v_add_f32_e32 v41, v41, v163
	v_cndmask_b32_e64 v41, v195, v41, s[62:63]
	v_exp_f32_e32 v41, v41
	v_add_f32_e32 v42, v42, v164
	v_cndmask_b32_e64 v42, v195, v42, s[38:39]
	v_exp_f32_e32 v42, v42
	v_add_f32_e32 v43, v43, v165
	v_cndmask_b32_e64 v43, v195, v43, s[44:45]
	v_exp_f32_e32 v43, v43
	v_add_f32_e32 v44, v44, v166
	v_cndmask_b32_e64 v44, v195, v44, s[56:57]
	v_exp_f32_e32 v44, v44
	v_add_f32_e32 v45, v45, v167
	v_cndmask_b32_e64 v45, v195, v45, s[82:83]
	v_exp_f32_e32 v45, v45
	v_add_f32_e32 v46, v46, v168
	v_cndmask_b32_e64 v46, v195, v46, s[84:85]
	v_exp_f32_e32 v46, v46
	v_add_f32_e32 v47, v47, v169
	v_cndmask_b32_e64 v47, v195, v47, s[2:3]
	v_exp_f32_e32 v47, v47
	v_add_f32_e32 v149, 0, v60
	v_add_f32_e32 v149, v149, v61
	v_add_f32_e32 v149, v149, v62
	v_add_f32_e32 v149, v149, v63
	v_add_f32_e32 v149, v149, v32
	v_add_f32_e32 v149, v149, v33
	v_add_f32_e32 v149, v149, v34
	v_add_f32_e32 v149, v149, v35
	v_add_f32_e32 v149, v149, v36
	v_add_f32_e32 v149, v149, v37
	v_add_f32_e32 v149, v149, v38
	v_add_f32_e32 v149, v149, v39
	v_add_f32_e32 v149, v149, v40
	v_add_f32_e32 v149, v149, v41
	v_add_f32_e32 v149, v149, v42
	v_add_f32_e32 v149, v149, v43
	v_add_f32_e32 v149, v149, v44
	v_add_f32_e32 v149, v149, v45
	v_add_f32_e32 v149, v149, v46
	v_add_f32_e32 v149, v149, v47
	v_cvt_pk_bf16_f32 v48, v40, v41
	v_cvt_pk_bf16_f32 v49, v42, v43
	v_cvt_pk_bf16_f32 v50, v44, v45
	v_cvt_pk_bf16_f32 v51, v46, v47
	v_cvt_pk_bf16_f32 v44, v32, v33
	v_cvt_pk_bf16_f32 v45, v34, v35
	v_cvt_pk_bf16_f32 v46, v36, v37
	v_cvt_pk_bf16_f32 v47, v38, v39
	v_cvt_pk_bf16_f32 v42, v60, v61
	v_cvt_pk_bf16_f32 v43, v62, v63
	v_mov_b32_e32 v40, 0
	v_mov_b32_e32 v41, 0
	v_mov_b32_e32 v33, v149
